# P0 items de-serialized (transpose rows, GEMV reduction, cache_k); attention item prologue loads batched
# speedup vs baseline: 1.0613x; 1.0131x over previous
.LBB0_10:
	v_cmp_lt_i32_e32 vcc, s48, v35
	s_barrier
	s_and_saveexec_b64 s[4:5], vcc
	s_xor_b64 s[36:37], exec, s[4:5]
	s_cbranch_execz .LBB0_50
	s_movk_i32 s3, 0xa3f
	v_cmp_lt_u32_e32 vcc, s3, v35
	s_and_saveexec_b64 s[4:5], vcc
	s_xor_b64 s[4:5], exec, s[4:5]
	s_cbranch_execz .LBB0_21
	s_movk_i32 s3, 0xb64
	v_cmp_gt_u32_e32 vcc, s3, v35
	v_lshlrev_b32_e32 v22, 12, v35
	s_and_saveexec_b64 s[10:11], vcc
	s_xor_b64 s[38:39], exec, s[10:11]
	s_cbranch_execz .LBB0_18
	s_movk_i32 s3, 0xb40
	v_cmp_gt_u32_e32 vcc, s3, v35
	s_and_saveexec_b64 s[10:11], vcc
	s_xor_b64 s[10:11], exec, s[10:11]
	s_cbranch_execz .LBB0_15
	v_add_u32_e32 v3, 0xff5c0000, v22
	v_or_b32_sdwa v2, v3, v212 dst_sel:DWORD dst_unused:UNUSED_PAD src0_sel:DWORD src1_sel:BYTE_0
	v_lshrrev_b32_e32 v3, 6, v3
	v_bfe_u32 v4, v35, 3, 3
	s_mov_b32 s3, 0x3fff000
	v_and_or_b32 v8, v3, s3, v4
	v_lshrrev_b32_e32 v3, 3, v2
	s_movk_i32 s3, 0xe18
	v_and_or_b32 v22, v3, s3, v8
	v_lshlrev_b64 v[4:5], 8, v[22:23]
	v_lshl_add_u64 v[4:5], v[24:25], 0, v[4:5]
	s_mov_b64 s[98:99], 0x2000
	global_load_dword v170, v[4:5], off
	v_lshl_add_u64 v[4:5], v[4:5], 0, s[98:99]
	global_load_dword v171, v[4:5], off
	v_lshl_add_u64 v[4:5], v[4:5], 0, s[98:99]
	global_load_dword v172, v[4:5], off
	v_lshl_add_u64 v[4:5], v[4:5], 0, s[98:99]
	global_load_dword v173, v[4:5], off
	v_lshl_add_u64 v[4:5], v[4:5], 0, s[98:99]
	global_load_dword v174, v[4:5], off
	v_lshl_add_u64 v[4:5], v[4:5], 0, s[98:99]
	global_load_dword v175, v[4:5], off
	v_lshl_add_u64 v[4:5], v[4:5], 0, s[98:99]
	global_load_dword v176, v[4:5], off
	v_lshl_add_u64 v[4:5], v[4:5], 0, s[98:99]
	global_load_dword v177, v[4:5], off
	v_lshl_add_u64 v[4:5], v[4:5], 0, s[98:99]
	global_load_dword v178, v[4:5], off
	v_lshl_add_u64 v[4:5], v[4:5], 0, s[98:99]
	global_load_dword v179, v[4:5], off
	v_lshl_add_u64 v[4:5], v[4:5], 0, s[98:99]
	global_load_dword v180, v[4:5], off
	v_lshl_add_u64 v[4:5], v[4:5], 0, s[98:99]
	global_load_dword v181, v[4:5], off
	v_lshl_add_u64 v[4:5], v[4:5], 0, s[98:99]
	global_load_dword v182, v[4:5], off
	v_lshl_add_u64 v[4:5], v[4:5], 0, s[98:99]
	global_load_dword v183, v[4:5], off
	v_lshl_add_u64 v[4:5], v[4:5], 0, s[98:99]
	global_load_dword v184, v[4:5], off
	v_lshl_add_u64 v[4:5], v[4:5], 0, s[98:99]
	global_load_dword v185, v[4:5], off
	v_mov_b32_e32 v3, v23
	v_lshl_add_u64 v[4:5], v[2:3], 1, s[14:15]
	s_mov_b64 s[98:99], 0x1000
	v_lshl_add_u64 v[6:7], v[4:5], 0, s[98:99]
	s_waitcnt vmcnt(15)
	v_cvt_pk_bf16_f32 v186, v170, s0
	global_store_short v[4:5], v186, off
	s_waitcnt vmcnt(15)
	v_cvt_pk_bf16_f32 v187, v171, s0
	global_store_short v[4:5], v187, off offset:512
	s_waitcnt vmcnt(15)
	v_cvt_pk_bf16_f32 v188, v172, s0
	global_store_short v[4:5], v188, off offset:1024
	s_waitcnt vmcnt(15)
	v_cvt_pk_bf16_f32 v189, v173, s0
	global_store_short v[4:5], v189, off offset:1536
	s_waitcnt vmcnt(15)
	v_cvt_pk_bf16_f32 v190, v174, s0
	global_store_short v[4:5], v190, off offset:2048
	s_waitcnt vmcnt(15)
	v_cvt_pk_bf16_f32 v191, v175, s0
	global_store_short v[4:5], v191, off offset:2560
	s_waitcnt vmcnt(15)
	v_cvt_pk_bf16_f32 v192, v176, s0
	global_store_short v[4:5], v192, off offset:3072
	s_waitcnt vmcnt(15)
	v_cvt_pk_bf16_f32 v193, v177, s0
	global_store_short v[4:5], v193, off offset:3584
	s_waitcnt vmcnt(15)
	v_cvt_pk_bf16_f32 v194, v178, s0
	global_store_short v[6:7], v194, off
	s_waitcnt vmcnt(15)
	v_cvt_pk_bf16_f32 v195, v179, s0
	global_store_short v[6:7], v195, off offset:512
	s_waitcnt vmcnt(15)
	v_cvt_pk_bf16_f32 v196, v180, s0
	global_store_short v[6:7], v196, off offset:1024
	s_waitcnt vmcnt(15)
	v_cvt_pk_bf16_f32 v197, v181, s0
	global_store_short v[6:7], v197, off offset:1536
	s_waitcnt vmcnt(15)
	v_cvt_pk_bf16_f32 v198, v182, s0
	global_store_short v[6:7], v198, off offset:2048
	s_waitcnt vmcnt(15)
	v_cvt_pk_bf16_f32 v199, v183, s0
	global_store_short v[6:7], v199, off offset:2560
	s_waitcnt vmcnt(15)
	v_cvt_pk_bf16_f32 v200, v184, s0
	global_store_short v[6:7], v200, off offset:3072
	s_waitcnt vmcnt(15)
	v_cvt_pk_bf16_f32 v201, v185, s0
	global_store_short v[6:7], v201, off offset:3584

.LBB0_48:
	s_or_b64 exec, exec, s[4:5]
	v_or_b32_e32 v5, v12, v34
	v_mad_u64_u32 v[12:13], s[4:5], v10, v5, 0
	v_mov_b32_e32 v14, v13
	v_mad_u64_u32 v[14:15], s[4:5], v11, v5, v[14:15]
	v_lshl_add_u64 v[8:9], v[22:23], 2, v[8:9]
	v_mov_b32_e32 v13, v14
	v_lshl_add_u64 v[12:13], v[12:13], 2, v[8:9]
	v_lshlrev_b64 v[162:163], 6, v[10:11]
	v_lshl_add_u64 v[164:165], v[12:13], 0, v[162:163]
	v_lshl_add_u64 v[166:167], v[164:165], 0, v[162:163]
	v_lshl_add_u64 v[168:169], v[166:167], 0, v[162:163]
	global_load_dwordx4 v[170:173], v[12:13], off
	global_load_dwordx4 v[174:177], v[164:165], off
	global_load_dwordx4 v[178:181], v[166:167], off
	global_load_dwordx4 v[182:185], v[168:169], off
	v_or_b32_e32 v7, v7, v54
	v_mov_b32_e32 v45, v23
	v_add_u32_e32 v5, 0x400, v55
	s_waitcnt vmcnt(3)
	ds_write_b128 v65, v[170:173]
	s_waitcnt vmcnt(2)
	ds_write_b128 v65, v[174:177] offset:4352
	s_waitcnt vmcnt(1)
	ds_write_b128 v65, v[178:181] offset:8704
	s_waitcnt vmcnt(0)
	ds_write_b128 v65, v[182:185] offset:13056
	s_waitcnt lgkmcnt(0)
	s_barrier
	ds_read2_b32 v[8:9], v55 offset1:136
	ds_read2_b32 v[10:11], v57 offset0:68 offset1:204
	s_waitcnt lgkmcnt(0)
	v_cvt_pk_bf16_f32 v8, v8, v10
	v_cvt_pk_bf16_f32 v9, v9, v11
	ds_read2_b32 v[10:11], v5 offset0:16 offset1:152
	v_add_u32_e32 v5, 0x400, v57
	ds_read2_b32 v[12:13], v5 offset0:84 offset1:220
	v_add_u32_e32 v5, 0x800, v55
	s_waitcnt lgkmcnt(0)
	v_cvt_pk_bf16_f32 v10, v10, v12
	v_cvt_pk_bf16_f32 v11, v11, v13
	ds_read2_b32 v[12:13], v5 offset0:32 offset1:168
	v_add_u32_e32 v5, 0x800, v57
	ds_read2_b32 v[14:15], v5 offset0:100 offset1:236
	v_add_u32_e32 v5, 0xc00, v55
	s_waitcnt lgkmcnt(0)
	v_cvt_pk_bf16_f32 v12, v12, v14
	v_cvt_pk_bf16_f32 v13, v13, v15
	ds_read2_b32 v[14:15], v5 offset0:48 offset1:184
	v_add_u32_e32 v5, 0xc00, v57
	ds_read2_b32 v[16:17], v5 offset0:116 offset1:252
	v_mul_hi_u32_u24_e32 v5, v4, v7
	v_mul_u32_u24_e32 v4, v4, v7
	v_lshl_add_u64 v[2:3], v[4:5], 1, v[2:3]
	v_mov_b32_e32 v7, v23
	v_lshl_add_u64 v[2:3], v[6:7], 1, v[2:3]
	v_lshl_add_u64 v[2:3], v[2:3], 0, v[44:45]
	s_waitcnt lgkmcnt(0)
	v_cvt_pk_bf16_f32 v14, v14, v16
	v_cvt_pk_bf16_f32 v15, v15, v17
	global_store_dwordx4 v[2:3], v[8:11], off
	global_store_dwordx4 v[2:3], v[12:15], off offset:16

.LBB0_50:
	s_andn2_saveexec_b64 s[10:11], s[36:37]
	s_cbranch_execz .LBB0_9
	v_readlane_b32 s16, v245, 32
	s_mov_b64 s[4:5], 0
	v_readlane_b32 s24, v245, 40
	v_readlane_b32 s25, v245, 41
	v_readlane_b32 s30, v245, 46
	v_readlane_b32 s31, v245, 47
	v_readlane_b32 s17, v245, 33
	v_readlane_b32 s18, v245, 34
	v_readlane_b32 s19, v245, 35
	v_readlane_b32 s20, v245, 36
	v_readlane_b32 s21, v245, 37
	v_readlane_b32 s22, v245, 38
	v_readlane_b32 s23, v245, 39
	v_readlane_b32 s26, v245, 42
	v_readlane_b32 s27, v245, 43
	v_readlane_b32 s28, v245, 44
	v_readlane_b32 s29, v245, 45
	global_load_dword v170, v[36:37], off
	global_load_dword v171, v[36:37], off offset:1024
	global_load_dword v172, v[36:37], off offset:2048
	global_load_dword v173, v[38:39], off
	v_and_b32_e32 v168, 0xff, v212
	v_lshlrev_b32_e32 v168, 2, v168
	global_load_dword v174, v168, s[24:25]
	global_load_dword v175, v168, s[24:25] offset:1024
	global_load_dword v176, v168, s[24:25] offset:2048
	global_load_dword v177, v168, s[24:25] offset:3072
	v_add_u32_e32 v168, 0x1000, v168
	global_load_dword v178, v168, s[24:25]
	global_load_dword v179, v168, s[24:25] offset:1024
	global_load_dword v180, v168, s[24:25] offset:2048
	global_load_dword v181, v168, s[24:25] offset:3072
	v_add_u32_e32 v168, 0x1000, v168
	global_load_dword v182, v168, s[24:25]
	global_load_dword v183, v168, s[24:25] offset:1024
	global_load_dword v184, v168, s[24:25] offset:2048
	global_load_dword v185, v168, s[24:25] offset:3072
	v_add_u32_e32 v168, 0x1000, v168
	global_load_dword v186, v168, s[24:25]
	global_load_dword v187, v168, s[24:25] offset:1024
	global_load_dword v188, v168, s[24:25] offset:2048
	global_load_dword v189, v168, s[24:25] offset:3072
	s_waitcnt vmcnt(0)
	v_mul_f32_e32 v190, 0xbfb8aa3b, v170
	v_mul_f32_e32 v191, 0xbfb8aa3b, v171
	v_mul_f32_e32 v192, 0xbfb8aa3b, v172
	v_mul_f32_e32 v193, 0xbfb8aa3b, v173
	v_mul_f32_e32 v194, 0xbfb8aa3b, v174
	v_mul_f32_e32 v195, 0xbfb8aa3b, v175
	v_mul_f32_e32 v196, 0xbfb8aa3b, v176
	v_mul_f32_e32 v197, 0xbfb8aa3b, v177
	v_mul_f32_e32 v198, 0xbfb8aa3b, v178
	v_mul_f32_e32 v199, 0xbfb8aa3b, v179
	v_mul_f32_e32 v200, 0xbfb8aa3b, v180
	v_mul_f32_e32 v201, 0xbfb8aa3b, v181
	v_mul_f32_e32 v202, 0xbfb8aa3b, v182
	v_mul_f32_e32 v203, 0xbfb8aa3b, v183
	v_mul_f32_e32 v204, 0xbfb8aa3b, v184
	v_mul_f32_e32 v205, 0xbfb8aa3b, v185
	v_mul_f32_e32 v206, 0xbfb8aa3b, v186
	v_mul_f32_e32 v207, 0xbfb8aa3b, v187
	v_mul_f32_e32 v208, 0xbfb8aa3b, v188
	v_mul_f32_e32 v209, 0xbfb8aa3b, v189
	v_exp_f32_e32 v190, v190
	v_exp_f32_e32 v191, v191
	v_exp_f32_e32 v192, v192
	v_exp_f32_e32 v193, v193
	v_exp_f32_e32 v194, v194
	v_exp_f32_e32 v195, v195
	v_exp_f32_e32 v196, v196
	v_exp_f32_e32 v197, v197
	v_exp_f32_e32 v198, v198
	v_exp_f32_e32 v199, v199
	v_exp_f32_e32 v200, v200
	v_exp_f32_e32 v201, v201
	v_exp_f32_e32 v202, v202
	v_exp_f32_e32 v203, v203
	v_exp_f32_e32 v204, v204
	v_exp_f32_e32 v205, v205
	v_exp_f32_e32 v206, v206
	v_exp_f32_e32 v207, v207
	v_exp_f32_e32 v208, v208
	v_exp_f32_e32 v209, v209
	v_add_f32_e32 v190, 1.0, v190
	v_add_f32_e32 v191, 1.0, v191
	v_add_f32_e32 v192, 1.0, v192
	v_add_f32_e32 v193, 1.0, v193
	v_add_f32_e32 v194, 1.0, v194
	v_add_f32_e32 v195, 1.0, v195
	v_add_f32_e32 v196, 1.0, v196
	v_add_f32_e32 v197, 1.0, v197
	v_add_f32_e32 v198, 1.0, v198
	v_add_f32_e32 v199, 1.0, v199
	v_add_f32_e32 v200, 1.0, v200
	v_add_f32_e32 v201, 1.0, v201
	v_add_f32_e32 v202, 1.0, v202
	v_add_f32_e32 v203, 1.0, v203
	v_add_f32_e32 v204, 1.0, v204
	v_add_f32_e32 v205, 1.0, v205
	v_add_f32_e32 v206, 1.0, v206
	v_add_f32_e32 v207, 1.0, v207
	v_add_f32_e32 v208, 1.0, v208
	v_add_f32_e32 v209, 1.0, v209
	v_rcp_f32_e32 v190, v190
	v_rcp_f32_e32 v191, v191
	v_rcp_f32_e32 v192, v192
	v_rcp_f32_e32 v193, v193
	v_rcp_f32_e32 v194, v194
	v_rcp_f32_e32 v195, v195
	v_rcp_f32_e32 v196, v196
	v_rcp_f32_e32 v197, v197
	v_rcp_f32_e32 v198, v198
	v_rcp_f32_e32 v199, v199
	v_rcp_f32_e32 v200, v200
	v_rcp_f32_e32 v201, v201
	v_rcp_f32_e32 v202, v202
	v_rcp_f32_e32 v203, v203
	v_rcp_f32_e32 v204, v204
	v_rcp_f32_e32 v205, v205
	v_rcp_f32_e32 v206, v206
	v_rcp_f32_e32 v207, v207
	v_rcp_f32_e32 v208, v208
	v_rcp_f32_e32 v209, v209
	v_mul_f32_e32 v170, v170, v190
	v_mul_f32_e32 v171, v171, v191
	v_mul_f32_e32 v172, v172, v192
	v_mul_f32_e32 v173, v173, v193
	v_mul_f32_e32 v174, v174, v194
	v_mul_f32_e32 v175, v175, v195
	v_mul_f32_e32 v176, v176, v196
	v_mul_f32_e32 v177, v177, v197
	v_mul_f32_e32 v178, v178, v198
	v_mul_f32_e32 v179, v179, v199
	v_mul_f32_e32 v180, v180, v200
	v_mul_f32_e32 v181, v181, v201
	v_mul_f32_e32 v182, v182, v202
	v_mul_f32_e32 v183, v183, v203
	v_mul_f32_e32 v184, v184, v204
	v_mul_f32_e32 v185, v185, v205
	v_mul_f32_e32 v186, v186, v206
	v_mul_f32_e32 v187, v187, v207
	v_mul_f32_e32 v188, v188, v208
	v_mul_f32_e32 v189, v189, v209
	ds_write_b32 v58, v170
	ds_write_b32 v58, v171 offset:1024
	ds_write_b32 v58, v172 offset:2048
	ds_write_b32 v58, v173 offset:3072
	ds_write_b32 v58, v174 offset:4096
	ds_write_b32 v58, v175 offset:5120
	ds_write_b32 v58, v176 offset:6144
	ds_write_b32 v58, v177 offset:7168
	ds_write_b32 v58, v178 offset:8192
	ds_write_b32 v58, v179 offset:9216
	ds_write_b32 v58, v180 offset:10240
	ds_write_b32 v58, v181 offset:11264
	ds_write_b32 v58, v182 offset:12288
	ds_write_b32 v58, v183 offset:13312
	ds_write_b32 v58, v184 offset:14336
	ds_write_b32 v58, v185 offset:15360
	ds_write_b32 v58, v186 offset:16384
	ds_write_b32 v58, v187 offset:17408
	ds_write_b32 v58, v188 offset:18432
	ds_write_b32 v58, v189 offset:19456
	s_or_b64 exec, exec, s[4:5]
	s_mov_b32 s3, 0x2aaaaaab
	v_mul_hi_i32 v2, v35, s3
	v_lshrrev_b32_e32 v3, 31, v2
	v_ashrrev_i32_e32 v2, 5, v2
	v_add_u32_e32 v22, v2, v3
	s_movk_i32 s3, 0xc0
	v_mul_lo_u32 v2, v22, s3
	v_sub_u32_e32 v2, v35, v2
	v_readlane_b32 s80, v245, 0
	v_lshlrev_b32_e32 v46, 4, v2
	v_add_u32_e32 v2, 0xbf, v35
	v_readlane_b32 s87, v245, 7
	v_readlane_b32 s86, v245, 6
	v_mov_b32_e32 v4, s31
	v_mov_b32_e32 v3, s87
	v_cmp_gt_u32_e32 vcc, s48, v2
	v_mov_b32_e32 v2, s86
	v_ashrrev_i32_e32 v47, 31, v46
	v_cndmask_b32_e32 v3, v3, v4, vcc
	v_mov_b32_e32 v4, s30
	v_cndmask_b32_e32 v2, v2, v4, vcc
	v_lshl_add_u64 v[2:3], v[2:3], 0, v[40:41]
	v_mov_b32_e32 v6, 0
	v_lshl_add_u64 v[48:49], v[46:47], 2, v[2:3]
	s_mov_b64 s[36:37], 0
	v_mov_b32_e32 v43, v56
	v_mov_b32_e32 v7, v6
	v_mov_b32_e32 v8, v6
	v_mov_b32_e32 v9, v6
	v_mov_b32_e32 v18, v6
	v_mov_b32_e32 v19, v6
	v_mov_b32_e32 v20, v6
	v_mov_b32_e32 v21, v6
	v_mov_b32_e32 v14, v6
	v_mov_b32_e32 v15, v6
	v_mov_b32_e32 v16, v6
	v_mov_b32_e32 v17, v6
	v_mov_b32_e32 v10, v6
	v_mov_b32_e32 v11, v6
	v_mov_b32_e32 v12, v6
	v_mov_b32_e32 v13, v6
	v_mov_b32_e32 v2, v6
	v_mov_b32_e32 v3, v6
	v_mov_b32_e32 v4, v6
	v_mov_b32_e32 v5, v6
	s_waitcnt lgkmcnt(0)
	s_barrier
	v_readlane_b32 s81, v245, 1
	v_readlane_b32 s82, v245, 2
	v_readlane_b32 s83, v245, 3
	v_readlane_b32 s84, v245, 4
	v_readlane_b32 s85, v245, 5
	v_readlane_b32 s88, v245, 8
	v_readlane_b32 s89, v245, 9
	v_readlane_b32 s90, v245, 10
	v_readlane_b32 s91, v245, 11
	v_readlane_b32 s92, v245, 12
	v_readlane_b32 s93, v245, 13
	v_readlane_b32 s94, v245, 14
	v_readlane_b32 s95, v245, 15
	s_mov_b64 s[98:99], 0xc0000
	v_mov_b32_e32 v50, v48
	v_mov_b32_e32 v51, v49
	global_load_dwordx4 v[162:165], v[50:51], off
	v_lshl_add_u64 v[50:51], v[50:51], 0, s[98:99]
	global_load_dwordx4 v[166:169], v[50:51], off
	v_lshl_add_u64 v[50:51], v[50:51], 0, s[98:99]
	global_load_dwordx4 v[170:173], v[50:51], off
	v_lshl_add_u64 v[50:51], v[50:51], 0, s[98:99]
	global_load_dwordx4 v[174:177], v[50:51], off
	v_lshl_add_u64 v[50:51], v[50:51], 0, s[98:99]
	global_load_dwordx4 v[178:181], v[50:51], off
	v_lshl_add_u64 v[50:51], v[50:51], 0, s[98:99]
	global_load_dwordx4 v[182:185], v[50:51], off
	v_lshl_add_u64 v[50:51], v[50:51], 0, s[98:99]
	global_load_dwordx4 v[186:189], v[50:51], off
	v_lshl_add_u64 v[50:51], v[50:51], 0, s[98:99]
	global_load_dwordx4 v[190:193], v[50:51], off
	v_lshl_add_u64 v[50:51], v[50:51], 0, s[98:99]
	global_load_dwordx4 v[194:197], v[50:51], off
	v_lshl_add_u64 v[50:51], v[50:51], 0, s[98:99]
	global_load_dwordx4 v[198:201], v[50:51], off
	v_lshl_add_u64 v[50:51], v[50:51], 0, s[98:99]
	global_load_dwordx4 v[202:205], v[50:51], off
	v_lshl_add_u64 v[50:51], v[50:51], 0, s[98:99]
	global_load_dwordx4 v[206:209], v[50:51], off
	v_lshl_add_u64 v[50:51], v[50:51], 0, s[98:99]
	global_load_dwordx4 v[214:217], v[50:51], off
	v_lshl_add_u64 v[50:51], v[50:51], 0, s[98:99]
	global_load_dwordx4 v[218:221], v[50:51], off
	v_lshl_add_u64 v[50:51], v[50:51], 0, s[98:99]
	global_load_dwordx4 v[222:225], v[50:51], off
	v_lshl_add_u64 v[50:51], v[50:51], 0, s[98:99]
	global_load_dwordx4 v[226:229], v[50:51], off
	ds_read2st64_b32 v[144:145], v43 offset0:0 offset1:1
	ds_read2st64_b32 v[146:147], v43 offset0:16 offset1:17
	ds_read2st64_b32 v[148:149], v43 offset0:32 offset1:33
	ds_read2st64_b32 v[150:151], v43 offset0:48 offset1:49
	ds_read2st64_b32 v[152:153], v43 offset0:64 offset1:65
	ds_read2st64_b32 v[230:231], v43 offset0:2 offset1:3
	ds_read2st64_b32 v[232:233], v43 offset0:18 offset1:19
	ds_read2st64_b32 v[234:235], v43 offset0:34 offset1:35
	ds_read2st64_b32 v[236:237], v43 offset0:50 offset1:51
	ds_read2st64_b32 v[238:239], v43 offset0:66 offset1:67
	s_waitcnt vmcnt(15) lgkmcnt(5)
	v_pk_fma_f32 v[6:7], v[162:163], v[144:145], v[6:7] op_sel_hi:[1,0,1]
	v_pk_fma_f32 v[8:9], v[164:165], v[144:145], v[8:9] op_sel_hi:[1,0,1]
	v_pk_fma_f32 v[18:19], v[162:163], v[146:147], v[18:19] op_sel_hi:[1,0,1]
	v_pk_fma_f32 v[20:21], v[164:165], v[146:147], v[20:21] op_sel_hi:[1,0,1]
	v_pk_fma_f32 v[14:15], v[162:163], v[148:149], v[14:15] op_sel_hi:[1,0,1]
	v_pk_fma_f32 v[16:17], v[164:165], v[148:149], v[16:17] op_sel_hi:[1,0,1]
	v_pk_fma_f32 v[10:11], v[162:163], v[150:151], v[10:11] op_sel_hi:[1,0,1]
	v_pk_fma_f32 v[12:13], v[164:165], v[150:151], v[12:13] op_sel_hi:[1,0,1]
	v_pk_fma_f32 v[2:3], v[162:163], v[152:153], v[2:3] op_sel_hi:[1,0,1]
	v_pk_fma_f32 v[4:5], v[164:165], v[152:153], v[4:5] op_sel_hi:[1,0,1]
	s_waitcnt vmcnt(14)
	v_pk_fma_f32 v[6:7], v[166:167], v[144:145], v[6:7] op_sel:[0,1,0] op_sel_hi:[1,1,1]
	v_pk_fma_f32 v[8:9], v[168:169], v[144:145], v[8:9] op_sel:[0,1,0] op_sel_hi:[1,1,1]
	v_pk_fma_f32 v[18:19], v[166:167], v[146:147], v[18:19] op_sel:[0,1,0] op_sel_hi:[1,1,1]
	v_pk_fma_f32 v[20:21], v[168:169], v[146:147], v[20:21] op_sel:[0,1,0] op_sel_hi:[1,1,1]
	v_pk_fma_f32 v[14:15], v[166:167], v[148:149], v[14:15] op_sel:[0,1,0] op_sel_hi:[1,1,1]
	v_pk_fma_f32 v[16:17], v[168:169], v[148:149], v[16:17] op_sel:[0,1,0] op_sel_hi:[1,1,1]
	v_pk_fma_f32 v[10:11], v[166:167], v[150:151], v[10:11] op_sel:[0,1,0] op_sel_hi:[1,1,1]
	v_pk_fma_f32 v[12:13], v[168:169], v[150:151], v[12:13] op_sel:[0,1,0] op_sel_hi:[1,1,1]
	v_pk_fma_f32 v[2:3], v[166:167], v[152:153], v[2:3] op_sel:[0,1,0] op_sel_hi:[1,1,1]
	v_pk_fma_f32 v[4:5], v[168:169], v[152:153], v[4:5] op_sel:[0,1,0] op_sel_hi:[1,1,1]
	ds_read2st64_b32 v[144:145], v43 offset0:4 offset1:5
	ds_read2st64_b32 v[146:147], v43 offset0:20 offset1:21
	ds_read2st64_b32 v[148:149], v43 offset0:36 offset1:37
	ds_read2st64_b32 v[150:151], v43 offset0:52 offset1:53
	ds_read2st64_b32 v[152:153], v43 offset0:68 offset1:69
	s_waitcnt vmcnt(13) lgkmcnt(5)
	v_pk_fma_f32 v[6:7], v[170:171], v[230:231], v[6:7] op_sel_hi:[1,0,1]
	v_pk_fma_f32 v[8:9], v[172:173], v[230:231], v[8:9] op_sel_hi:[1,0,1]
	v_pk_fma_f32 v[18:19], v[170:171], v[232:233], v[18:19] op_sel_hi:[1,0,1]
	v_pk_fma_f32 v[20:21], v[172:173], v[232:233], v[20:21] op_sel_hi:[1,0,1]
	v_pk_fma_f32 v[14:15], v[170:171], v[234:235], v[14:15] op_sel_hi:[1,0,1]
	v_pk_fma_f32 v[16:17], v[172:173], v[234:235], v[16:17] op_sel_hi:[1,0,1]
	v_pk_fma_f32 v[10:11], v[170:171], v[236:237], v[10:11] op_sel_hi:[1,0,1]
	v_pk_fma_f32 v[12:13], v[172:173], v[236:237], v[12:13] op_sel_hi:[1,0,1]
	v_pk_fma_f32 v[2:3], v[170:171], v[238:239], v[2:3] op_sel_hi:[1,0,1]
	v_pk_fma_f32 v[4:5], v[172:173], v[238:239], v[4:5] op_sel_hi:[1,0,1]
	s_waitcnt vmcnt(12)
	v_pk_fma_f32 v[6:7], v[174:175], v[230:231], v[6:7] op_sel:[0,1,0] op_sel_hi:[1,1,1]
	v_pk_fma_f32 v[8:9], v[176:177], v[230:231], v[8:9] op_sel:[0,1,0] op_sel_hi:[1,1,1]
	v_pk_fma_f32 v[18:19], v[174:175], v[232:233], v[18:19] op_sel:[0,1,0] op_sel_hi:[1,1,1]
	v_pk_fma_f32 v[20:21], v[176:177], v[232:233], v[20:21] op_sel:[0,1,0] op_sel_hi:[1,1,1]
	v_pk_fma_f32 v[14:15], v[174:175], v[234:235], v[14:15] op_sel:[0,1,0] op_sel_hi:[1,1,1]
	v_pk_fma_f32 v[16:17], v[176:177], v[234:235], v[16:17] op_sel:[0,1,0] op_sel_hi:[1,1,1]
	v_pk_fma_f32 v[10:11], v[174:175], v[236:237], v[10:11] op_sel:[0,1,0] op_sel_hi:[1,1,1]
	v_pk_fma_f32 v[12:13], v[176:177], v[236:237], v[12:13] op_sel:[0,1,0] op_sel_hi:[1,1,1]
	v_pk_fma_f32 v[2:3], v[174:175], v[238:239], v[2:3] op_sel:[0,1,0] op_sel_hi:[1,1,1]
	v_pk_fma_f32 v[4:5], v[176:177], v[238:239], v[4:5] op_sel:[0,1,0] op_sel_hi:[1,1,1]
	ds_read2st64_b32 v[230:231], v43 offset0:6 offset1:7
	ds_read2st64_b32 v[232:233], v43 offset0:22 offset1:23
	ds_read2st64_b32 v[234:235], v43 offset0:38 offset1:39
	ds_read2st64_b32 v[236:237], v43 offset0:54 offset1:55
	ds_read2st64_b32 v[238:239], v43 offset0:70 offset1:71
	s_waitcnt vmcnt(11) lgkmcnt(5)
	v_pk_fma_f32 v[6:7], v[178:179], v[144:145], v[6:7] op_sel_hi:[1,0,1]
	v_pk_fma_f32 v[8:9], v[180:181], v[144:145], v[8:9] op_sel_hi:[1,0,1]
	v_pk_fma_f32 v[18:19], v[178:179], v[146:147], v[18:19] op_sel_hi:[1,0,1]
	v_pk_fma_f32 v[20:21], v[180:181], v[146:147], v[20:21] op_sel_hi:[1,0,1]
	v_pk_fma_f32 v[14:15], v[178:179], v[148:149], v[14:15] op_sel_hi:[1,0,1]
	v_pk_fma_f32 v[16:17], v[180:181], v[148:149], v[16:17] op_sel_hi:[1,0,1]
	v_pk_fma_f32 v[10:11], v[178:179], v[150:151], v[10:11] op_sel_hi:[1,0,1]
	v_pk_fma_f32 v[12:13], v[180:181], v[150:151], v[12:13] op_sel_hi:[1,0,1]
	v_pk_fma_f32 v[2:3], v[178:179], v[152:153], v[2:3] op_sel_hi:[1,0,1]
	v_pk_fma_f32 v[4:5], v[180:181], v[152:153], v[4:5] op_sel_hi:[1,0,1]
	s_waitcnt vmcnt(10)
	v_pk_fma_f32 v[6:7], v[182:183], v[144:145], v[6:7] op_sel:[0,1,0] op_sel_hi:[1,1,1]
	v_pk_fma_f32 v[8:9], v[184:185], v[144:145], v[8:9] op_sel:[0,1,0] op_sel_hi:[1,1,1]
	v_pk_fma_f32 v[18:19], v[182:183], v[146:147], v[18:19] op_sel:[0,1,0] op_sel_hi:[1,1,1]
	v_pk_fma_f32 v[20:21], v[184:185], v[146:147], v[20:21] op_sel:[0,1,0] op_sel_hi:[1,1,1]
	v_pk_fma_f32 v[14:15], v[182:183], v[148:149], v[14:15] op_sel:[0,1,0] op_sel_hi:[1,1,1]
	v_pk_fma_f32 v[16:17], v[184:185], v[148:149], v[16:17] op_sel:[0,1,0] op_sel_hi:[1,1,1]
	v_pk_fma_f32 v[10:11], v[182:183], v[150:151], v[10:11] op_sel:[0,1,0] op_sel_hi:[1,1,1]
	v_pk_fma_f32 v[12:13], v[184:185], v[150:151], v[12:13] op_sel:[0,1,0] op_sel_hi:[1,1,1]
	v_pk_fma_f32 v[2:3], v[182:183], v[152:153], v[2:3] op_sel:[0,1,0] op_sel_hi:[1,1,1]
	v_pk_fma_f32 v[4:5], v[184:185], v[152:153], v[4:5] op_sel:[0,1,0] op_sel_hi:[1,1,1]
	ds_read2st64_b32 v[144:145], v43 offset0:8 offset1:9
	ds_read2st64_b32 v[146:147], v43 offset0:24 offset1:25
	ds_read2st64_b32 v[148:149], v43 offset0:40 offset1:41
	ds_read2st64_b32 v[150:151], v43 offset0:56 offset1:57
	ds_read2st64_b32 v[152:153], v43 offset0:72 offset1:73
	s_waitcnt vmcnt(9) lgkmcnt(5)
	v_pk_fma_f32 v[6:7], v[186:187], v[230:231], v[6:7] op_sel_hi:[1,0,1]
	v_pk_fma_f32 v[8:9], v[188:189], v[230:231], v[8:9] op_sel_hi:[1,0,1]
	v_pk_fma_f32 v[18:19], v[186:187], v[232:233], v[18:19] op_sel_hi:[1,0,1]
	v_pk_fma_f32 v[20:21], v[188:189], v[232:233], v[20:21] op_sel_hi:[1,0,1]
	v_pk_fma_f32 v[14:15], v[186:187], v[234:235], v[14:15] op_sel_hi:[1,0,1]
	v_pk_fma_f32 v[16:17], v[188:189], v[234:235], v[16:17] op_sel_hi:[1,0,1]
	v_pk_fma_f32 v[10:11], v[186:187], v[236:237], v[10:11] op_sel_hi:[1,0,1]
	v_pk_fma_f32 v[12:13], v[188:189], v[236:237], v[12:13] op_sel_hi:[1,0,1]
	v_pk_fma_f32 v[2:3], v[186:187], v[238:239], v[2:3] op_sel_hi:[1,0,1]
	v_pk_fma_f32 v[4:5], v[188:189], v[238:239], v[4:5] op_sel_hi:[1,0,1]
	s_waitcnt vmcnt(8)
	v_pk_fma_f32 v[6:7], v[190:191], v[230:231], v[6:7] op_sel:[0,1,0] op_sel_hi:[1,1,1]
	v_pk_fma_f32 v[8:9], v[192:193], v[230:231], v[8:9] op_sel:[0,1,0] op_sel_hi:[1,1,1]
	v_pk_fma_f32 v[18:19], v[190:191], v[232:233], v[18:19] op_sel:[0,1,0] op_sel_hi:[1,1,1]
	v_pk_fma_f32 v[20:21], v[192:193], v[232:233], v[20:21] op_sel:[0,1,0] op_sel_hi:[1,1,1]
	v_pk_fma_f32 v[14:15], v[190:191], v[234:235], v[14:15] op_sel:[0,1,0] op_sel_hi:[1,1,1]
	v_pk_fma_f32 v[16:17], v[192:193], v[234:235], v[16:17] op_sel:[0,1,0] op_sel_hi:[1,1,1]
	v_pk_fma_f32 v[10:11], v[190:191], v[236:237], v[10:11] op_sel:[0,1,0] op_sel_hi:[1,1,1]
	v_pk_fma_f32 v[12:13], v[192:193], v[236:237], v[12:13] op_sel:[0,1,0] op_sel_hi:[1,1,1]
	v_pk_fma_f32 v[2:3], v[190:191], v[238:239], v[2:3] op_sel:[0,1,0] op_sel_hi:[1,1,1]
	v_pk_fma_f32 v[4:5], v[192:193], v[238:239], v[4:5] op_sel:[0,1,0] op_sel_hi:[1,1,1]
	ds_read2st64_b32 v[230:231], v43 offset0:10 offset1:11
	ds_read2st64_b32 v[232:233], v43 offset0:26 offset1:27
	ds_read2st64_b32 v[234:235], v43 offset0:42 offset1:43
	ds_read2st64_b32 v[236:237], v43 offset0:58 offset1:59
	ds_read2st64_b32 v[238:239], v43 offset0:74 offset1:75
	s_waitcnt vmcnt(7) lgkmcnt(5)
	v_pk_fma_f32 v[6:7], v[194:195], v[144:145], v[6:7] op_sel_hi:[1,0,1]
	v_pk_fma_f32 v[8:9], v[196:197], v[144:145], v[8:9] op_sel_hi:[1,0,1]
	v_pk_fma_f32 v[18:19], v[194:195], v[146:147], v[18:19] op_sel_hi:[1,0,1]
	v_pk_fma_f32 v[20:21], v[196:197], v[146:147], v[20:21] op_sel_hi:[1,0,1]
	v_pk_fma_f32 v[14:15], v[194:195], v[148:149], v[14:15] op_sel_hi:[1,0,1]
	v_pk_fma_f32 v[16:17], v[196:197], v[148:149], v[16:17] op_sel_hi:[1,0,1]
	v_pk_fma_f32 v[10:11], v[194:195], v[150:151], v[10:11] op_sel_hi:[1,0,1]
	v_pk_fma_f32 v[12:13], v[196:197], v[150:151], v[12:13] op_sel_hi:[1,0,1]
	v_pk_fma_f32 v[2:3], v[194:195], v[152:153], v[2:3] op_sel_hi:[1,0,1]
	v_pk_fma_f32 v[4:5], v[196:197], v[152:153], v[4:5] op_sel_hi:[1,0,1]
	s_waitcnt vmcnt(6)
	v_pk_fma_f32 v[6:7], v[198:199], v[144:145], v[6:7] op_sel:[0,1,0] op_sel_hi:[1,1,1]
	v_pk_fma_f32 v[8:9], v[200:201], v[144:145], v[8:9] op_sel:[0,1,0] op_sel_hi:[1,1,1]
	v_pk_fma_f32 v[18:19], v[198:199], v[146:147], v[18:19] op_sel:[0,1,0] op_sel_hi:[1,1,1]
	v_pk_fma_f32 v[20:21], v[200:201], v[146:147], v[20:21] op_sel:[0,1,0] op_sel_hi:[1,1,1]
	v_pk_fma_f32 v[14:15], v[198:199], v[148:149], v[14:15] op_sel:[0,1,0] op_sel_hi:[1,1,1]
	v_pk_fma_f32 v[16:17], v[200:201], v[148:149], v[16:17] op_sel:[0,1,0] op_sel_hi:[1,1,1]
	v_pk_fma_f32 v[10:11], v[198:199], v[150:151], v[10:11] op_sel:[0,1,0] op_sel_hi:[1,1,1]
	v_pk_fma_f32 v[12:13], v[200:201], v[150:151], v[12:13] op_sel:[0,1,0] op_sel_hi:[1,1,1]
	v_pk_fma_f32 v[2:3], v[198:199], v[152:153], v[2:3] op_sel:[0,1,0] op_sel_hi:[1,1,1]
	v_pk_fma_f32 v[4:5], v[200:201], v[152:153], v[4:5] op_sel:[0,1,0] op_sel_hi:[1,1,1]
	ds_read2st64_b32 v[144:145], v43 offset0:12 offset1:13
	ds_read2st64_b32 v[146:147], v43 offset0:28 offset1:29
	ds_read2st64_b32 v[148:149], v43 offset0:44 offset1:45
	ds_read2st64_b32 v[150:151], v43 offset0:60 offset1:61
	ds_read2st64_b32 v[152:153], v43 offset0:76 offset1:77
	s_waitcnt vmcnt(5) lgkmcnt(5)
	v_pk_fma_f32 v[6:7], v[202:203], v[230:231], v[6:7] op_sel_hi:[1,0,1]
	v_pk_fma_f32 v[8:9], v[204:205], v[230:231], v[8:9] op_sel_hi:[1,0,1]
	v_pk_fma_f32 v[18:19], v[202:203], v[232:233], v[18:19] op_sel_hi:[1,0,1]
	v_pk_fma_f32 v[20:21], v[204:205], v[232:233], v[20:21] op_sel_hi:[1,0,1]
	v_pk_fma_f32 v[14:15], v[202:203], v[234:235], v[14:15] op_sel_hi:[1,0,1]
	v_pk_fma_f32 v[16:17], v[204:205], v[234:235], v[16:17] op_sel_hi:[1,0,1]
	v_pk_fma_f32 v[10:11], v[202:203], v[236:237], v[10:11] op_sel_hi:[1,0,1]
	v_pk_fma_f32 v[12:13], v[204:205], v[236:237], v[12:13] op_sel_hi:[1,0,1]
	v_pk_fma_f32 v[2:3], v[202:203], v[238:239], v[2:3] op_sel_hi:[1,0,1]
	v_pk_fma_f32 v[4:5], v[204:205], v[238:239], v[4:5] op_sel_hi:[1,0,1]
	s_waitcnt vmcnt(4)
	v_pk_fma_f32 v[6:7], v[206:207], v[230:231], v[6:7] op_sel:[0,1,0] op_sel_hi:[1,1,1]
	v_pk_fma_f32 v[8:9], v[208:209], v[230:231], v[8:9] op_sel:[0,1,0] op_sel_hi:[1,1,1]
	v_pk_fma_f32 v[18:19], v[206:207], v[232:233], v[18:19] op_sel:[0,1,0] op_sel_hi:[1,1,1]
	v_pk_fma_f32 v[20:21], v[208:209], v[232:233], v[20:21] op_sel:[0,1,0] op_sel_hi:[1,1,1]
	v_pk_fma_f32 v[14:15], v[206:207], v[234:235], v[14:15] op_sel:[0,1,0] op_sel_hi:[1,1,1]
	v_pk_fma_f32 v[16:17], v[208:209], v[234:235], v[16:17] op_sel:[0,1,0] op_sel_hi:[1,1,1]
	v_pk_fma_f32 v[10:11], v[206:207], v[236:237], v[10:11] op_sel:[0,1,0] op_sel_hi:[1,1,1]
	v_pk_fma_f32 v[12:13], v[208:209], v[236:237], v[12:13] op_sel:[0,1,0] op_sel_hi:[1,1,1]
	v_pk_fma_f32 v[2:3], v[206:207], v[238:239], v[2:3] op_sel:[0,1,0] op_sel_hi:[1,1,1]
	v_pk_fma_f32 v[4:5], v[208:209], v[238:239], v[4:5] op_sel:[0,1,0] op_sel_hi:[1,1,1]
	ds_read2st64_b32 v[230:231], v43 offset0:14 offset1:15
	ds_read2st64_b32 v[232:233], v43 offset0:30 offset1:31
	ds_read2st64_b32 v[234:235], v43 offset0:46 offset1:47
	ds_read2st64_b32 v[236:237], v43 offset0:62 offset1:63
	ds_read2st64_b32 v[238:239], v43 offset0:78 offset1:79
	s_waitcnt vmcnt(3) lgkmcnt(5)
	v_pk_fma_f32 v[6:7], v[214:215], v[144:145], v[6:7] op_sel_hi:[1,0,1]
	v_pk_fma_f32 v[8:9], v[216:217], v[144:145], v[8:9] op_sel_hi:[1,0,1]
	v_pk_fma_f32 v[18:19], v[214:215], v[146:147], v[18:19] op_sel_hi:[1,0,1]
	v_pk_fma_f32 v[20:21], v[216:217], v[146:147], v[20:21] op_sel_hi:[1,0,1]
	v_pk_fma_f32 v[14:15], v[214:215], v[148:149], v[14:15] op_sel_hi:[1,0,1]
	v_pk_fma_f32 v[16:17], v[216:217], v[148:149], v[16:17] op_sel_hi:[1,0,1]
	v_pk_fma_f32 v[10:11], v[214:215], v[150:151], v[10:11] op_sel_hi:[1,0,1]
	v_pk_fma_f32 v[12:13], v[216:217], v[150:151], v[12:13] op_sel_hi:[1,0,1]
	v_pk_fma_f32 v[2:3], v[214:215], v[152:153], v[2:3] op_sel_hi:[1,0,1]
	v_pk_fma_f32 v[4:5], v[216:217], v[152:153], v[4:5] op_sel_hi:[1,0,1]
	s_waitcnt vmcnt(2)
	v_pk_fma_f32 v[6:7], v[218:219], v[144:145], v[6:7] op_sel:[0,1,0] op_sel_hi:[1,1,1]
	v_pk_fma_f32 v[8:9], v[220:221], v[144:145], v[8:9] op_sel:[0,1,0] op_sel_hi:[1,1,1]
	v_pk_fma_f32 v[18:19], v[218:219], v[146:147], v[18:19] op_sel:[0,1,0] op_sel_hi:[1,1,1]
	v_pk_fma_f32 v[20:21], v[220:221], v[146:147], v[20:21] op_sel:[0,1,0] op_sel_hi:[1,1,1]
	v_pk_fma_f32 v[14:15], v[218:219], v[148:149], v[14:15] op_sel:[0,1,0] op_sel_hi:[1,1,1]
	v_pk_fma_f32 v[16:17], v[220:221], v[148:149], v[16:17] op_sel:[0,1,0] op_sel_hi:[1,1,1]
	v_pk_fma_f32 v[10:11], v[218:219], v[150:151], v[10:11] op_sel:[0,1,0] op_sel_hi:[1,1,1]
	v_pk_fma_f32 v[12:13], v[220:221], v[150:151], v[12:13] op_sel:[0,1,0] op_sel_hi:[1,1,1]
	v_pk_fma_f32 v[2:3], v[218:219], v[152:153], v[2:3] op_sel:[0,1,0] op_sel_hi:[1,1,1]
	v_pk_fma_f32 v[4:5], v[220:221], v[152:153], v[4:5] op_sel:[0,1,0] op_sel_hi:[1,1,1]
	s_waitcnt vmcnt(1) lgkmcnt(0)
	v_pk_fma_f32 v[6:7], v[222:223], v[230:231], v[6:7] op_sel_hi:[1,0,1]
	v_pk_fma_f32 v[8:9], v[224:225], v[230:231], v[8:9] op_sel_hi:[1,0,1]
	v_pk_fma_f32 v[18:19], v[222:223], v[232:233], v[18:19] op_sel_hi:[1,0,1]
	v_pk_fma_f32 v[20:21], v[224:225], v[232:233], v[20:21] op_sel_hi:[1,0,1]
	v_pk_fma_f32 v[14:15], v[222:223], v[234:235], v[14:15] op_sel_hi:[1,0,1]
	v_pk_fma_f32 v[16:17], v[224:225], v[234:235], v[16:17] op_sel_hi:[1,0,1]
	v_pk_fma_f32 v[10:11], v[222:223], v[236:237], v[10:11] op_sel_hi:[1,0,1]
	v_pk_fma_f32 v[12:13], v[224:225], v[236:237], v[12:13] op_sel_hi:[1,0,1]
	v_pk_fma_f32 v[2:3], v[222:223], v[238:239], v[2:3] op_sel_hi:[1,0,1]
	v_pk_fma_f32 v[4:5], v[224:225], v[238:239], v[4:5] op_sel_hi:[1,0,1]
	s_waitcnt vmcnt(0)
	v_pk_fma_f32 v[6:7], v[226:227], v[230:231], v[6:7] op_sel:[0,1,0] op_sel_hi:[1,1,1]
	v_pk_fma_f32 v[8:9], v[228:229], v[230:231], v[8:9] op_sel:[0,1,0] op_sel_hi:[1,1,1]
	v_pk_fma_f32 v[18:19], v[226:227], v[232:233], v[18:19] op_sel:[0,1,0] op_sel_hi:[1,1,1]
	v_pk_fma_f32 v[20:21], v[228:229], v[232:233], v[20:21] op_sel:[0,1,0] op_sel_hi:[1,1,1]
	v_pk_fma_f32 v[14:15], v[226:227], v[234:235], v[14:15] op_sel:[0,1,0] op_sel_hi:[1,1,1]
	v_pk_fma_f32 v[16:17], v[228:229], v[234:235], v[16:17] op_sel:[0,1,0] op_sel_hi:[1,1,1]
	v_pk_fma_f32 v[10:11], v[226:227], v[236:237], v[10:11] op_sel:[0,1,0] op_sel_hi:[1,1,1]
	v_pk_fma_f32 v[12:13], v[228:229], v[236:237], v[12:13] op_sel:[0,1,0] op_sel_hi:[1,1,1]
	v_pk_fma_f32 v[2:3], v[226:227], v[238:239], v[2:3] op_sel:[0,1,0] op_sel_hi:[1,1,1]
	v_pk_fma_f32 v[4:5], v[228:229], v[238:239], v[4:5] op_sel:[0,1,0] op_sel_hi:[1,1,1]
	ds_write_b128 v66, v[6:9] offset:20480
	ds_write_b128 v66, v[18:21] offset:20496
	ds_write_b128 v66, v[14:17] offset:20512
	ds_write_b128 v66, v[10:13] offset:20528
	ds_write_b128 v66, v[2:5] offset:20544
	s_waitcnt lgkmcnt(0)
	s_barrier
	s_and_saveexec_b64 s[4:5], s[68:69]
	s_cbranch_execz .LBB0_8
	v_readlane_b32 s80, v245, 0
	v_readlane_b32 s16, v245, 16
	v_readlane_b32 s89, v245, 9
	v_readlane_b32 s17, v245, 17
	v_readlane_b32 s88, v245, 8
	v_mov_b32_e32 v2, s89
	v_mov_b32_e32 v3, s17
	v_cndmask_b32_e32 v5, v2, v3, vcc
	v_mov_b32_e32 v2, s88
	v_mov_b32_e32 v3, s16
	v_cndmask_b32_e32 v4, v2, v3, vcc
	v_or_b32_e32 v2, v46, v60
	v_ashrrev_i32_e32 v3, 31, v2
	v_lshl_add_u64 v[4:5], v[2:3], 2, v[4:5]
	global_load_dword v3, v[4:5], off
	v_add_u32_e32 v4, v61, v62
	ds_read_b32 v4, v4 offset:20480
	s_movk_i32 s3, 0xc00
	v_readlane_b32 s81, v245, 1
	v_readlane_b32 s82, v245, 2
	v_readlane_b32 s83, v245, 3
	v_readlane_b32 s84, v245, 4
	v_readlane_b32 s85, v245, 5
	v_readlane_b32 s86, v245, 6
	v_readlane_b32 s87, v245, 7
	v_readlane_b32 s90, v245, 10
	v_readlane_b32 s91, v245, 11
	v_readlane_b32 s92, v245, 12
	v_readlane_b32 s93, v245, 13
	v_readlane_b32 s94, v245, 14
	v_readlane_b32 s95, v245, 15
	v_readlane_b32 s18, v245, 18
	v_readlane_b32 s19, v245, 19
	v_readlane_b32 s20, v245, 20
	v_readlane_b32 s21, v245, 21
	v_readlane_b32 s22, v245, 22
	v_readlane_b32 s23, v245, 23
	v_readlane_b32 s24, v245, 24
	v_readlane_b32 s25, v245, 25
	v_readlane_b32 s26, v245, 26
	v_readlane_b32 s27, v245, 27
	v_readlane_b32 s28, v245, 28
	v_readlane_b32 s29, v245, 29
	v_readlane_b32 s30, v245, 30
	v_readlane_b32 s31, v245, 31
	s_waitcnt vmcnt(0) lgkmcnt(0)
	v_add_f32_e32 v3, v3, v4
	ds_read_b32 v170, v67 offset:20480
	ds_read_b32 v171, v68 offset:20480
	ds_read_b32 v172, v69 offset:20480
	ds_read_b32 v173, v70 offset:20480
	ds_read_b32 v174, v71 offset:20480
	ds_read_b32 v175, v72 offset:20480
	ds_read_b32 v176, v73 offset:20480
	ds_read_b32 v177, v74 offset:20480
	ds_read_b32 v178, v75 offset:20480
	ds_read_b32 v179, v76 offset:20480
	ds_read_b32 v180, v77 offset:20480
	ds_read_b32 v181, v78 offset:20480
	ds_read_b32 v182, v79 offset:20480
	ds_read_b32 v183, v80 offset:20480
	ds_read_b32 v184, v81 offset:20480
	ds_read_b32 v185, v82 offset:20480
	s_waitcnt lgkmcnt(15)
	v_add_f32_e32 v3, v3, v170
	s_waitcnt lgkmcnt(14)
	v_add_f32_e32 v3, v3, v171
	s_waitcnt lgkmcnt(13)
	v_add_f32_e32 v3, v3, v172
	s_waitcnt lgkmcnt(12)
	v_add_f32_e32 v3, v3, v173
	s_waitcnt lgkmcnt(11)
	v_add_f32_e32 v3, v3, v174
	s_waitcnt lgkmcnt(10)
	v_add_f32_e32 v3, v3, v175
	s_waitcnt lgkmcnt(9)
	v_add_f32_e32 v3, v3, v176
	s_waitcnt lgkmcnt(8)
	v_add_f32_e32 v3, v3, v177
	s_waitcnt lgkmcnt(7)
	v_add_f32_e32 v3, v3, v178
	s_waitcnt lgkmcnt(6)
	v_add_f32_e32 v3, v3, v179
	s_waitcnt lgkmcnt(5)
	v_add_f32_e32 v3, v3, v180
	s_waitcnt lgkmcnt(4)
	v_add_f32_e32 v3, v3, v181
	s_waitcnt lgkmcnt(3)
	v_add_f32_e32 v3, v3, v182
	s_waitcnt lgkmcnt(2)
	v_add_f32_e32 v3, v3, v183
	s_waitcnt lgkmcnt(1)
	v_add_f32_e32 v3, v3, v184
	s_waitcnt lgkmcnt(0)
	v_add_f32_e32 v3, v3, v185
	ds_read_b32 v170, v83 offset:20480
	ds_read_b32 v171, v84 offset:20480
	ds_read_b32 v172, v85 offset:20480
	ds_read_b32 v173, v86 offset:20480
	ds_read_b32 v174, v87 offset:20480
	ds_read_b32 v175, v88 offset:20480
	ds_read_b32 v176, v89 offset:20480
	ds_read_b32 v177, v90 offset:20480
	ds_read_b32 v178, v91 offset:20480
	ds_read_b32 v179, v92 offset:20480
	ds_read_b32 v180, v93 offset:20480
	ds_read_b32 v181, v94 offset:20480
	ds_read_b32 v182, v95 offset:20480
	ds_read_b32 v183, v96 offset:20480
	ds_read_b32 v184, v97 offset:20480
	ds_read_b32 v185, v98 offset:20480
	s_waitcnt lgkmcnt(15)
	v_add_f32_e32 v3, v3, v170
	s_waitcnt lgkmcnt(14)
	v_add_f32_e32 v3, v3, v171
	s_waitcnt lgkmcnt(13)
	v_add_f32_e32 v3, v3, v172
	s_waitcnt lgkmcnt(12)
	v_add_f32_e32 v3, v3, v173
	s_waitcnt lgkmcnt(11)
	v_add_f32_e32 v3, v3, v174
	s_waitcnt lgkmcnt(10)
	v_add_f32_e32 v3, v3, v175
	s_waitcnt lgkmcnt(9)
	v_add_f32_e32 v3, v3, v176
	s_waitcnt lgkmcnt(8)
	v_add_f32_e32 v3, v3, v177
	s_waitcnt lgkmcnt(7)
	v_add_f32_e32 v3, v3, v178
	s_waitcnt lgkmcnt(6)
	v_add_f32_e32 v3, v3, v179
	s_waitcnt lgkmcnt(5)
	v_add_f32_e32 v3, v3, v180
	s_waitcnt lgkmcnt(4)
	v_add_f32_e32 v3, v3, v181
	s_waitcnt lgkmcnt(3)
	v_add_f32_e32 v3, v3, v182
	s_waitcnt lgkmcnt(2)
	v_add_f32_e32 v3, v3, v183
	s_waitcnt lgkmcnt(1)
	v_add_f32_e32 v3, v3, v184
	s_waitcnt lgkmcnt(0)
	v_add_f32_e32 v3, v3, v185
	ds_read_b32 v170, v99 offset:20480
	ds_read_b32 v171, v100 offset:20480
	ds_read_b32 v172, v101 offset:20480
	ds_read_b32 v173, v102 offset:20480
	ds_read_b32 v174, v103 offset:20480
	ds_read_b32 v175, v104 offset:20480
	ds_read_b32 v176, v105 offset:20480
	ds_read_b32 v177, v106 offset:20480
	ds_read_b32 v178, v107 offset:20480
	ds_read_b32 v179, v108 offset:20480
	ds_read_b32 v180, v109 offset:20480
	ds_read_b32 v181, v110 offset:20480
	ds_read_b32 v182, v111 offset:20480
	ds_read_b32 v183, v112 offset:20480
	ds_read_b32 v184, v113 offset:20480
	ds_read_b32 v185, v114 offset:20480
	s_waitcnt lgkmcnt(15)
	v_add_f32_e32 v3, v3, v170
	s_waitcnt lgkmcnt(14)
	v_add_f32_e32 v3, v3, v171
	s_waitcnt lgkmcnt(13)
	v_add_f32_e32 v3, v3, v172
	s_waitcnt lgkmcnt(12)
	v_add_f32_e32 v3, v3, v173
	s_waitcnt lgkmcnt(11)
	v_add_f32_e32 v3, v3, v174
	s_waitcnt lgkmcnt(10)
	v_add_f32_e32 v3, v3, v175
	s_waitcnt lgkmcnt(9)
	v_add_f32_e32 v3, v3, v176
	s_waitcnt lgkmcnt(8)
	v_add_f32_e32 v3, v3, v177
	s_waitcnt lgkmcnt(7)
	v_add_f32_e32 v3, v3, v178
	s_waitcnt lgkmcnt(6)
	v_add_f32_e32 v3, v3, v179
	s_waitcnt lgkmcnt(5)
	v_add_f32_e32 v3, v3, v180
	s_waitcnt lgkmcnt(4)
	v_add_f32_e32 v3, v3, v181
	s_waitcnt lgkmcnt(3)
	v_add_f32_e32 v3, v3, v182
	s_waitcnt lgkmcnt(2)
	v_add_f32_e32 v3, v3, v183
	s_waitcnt lgkmcnt(1)
	v_add_f32_e32 v3, v3, v184
	s_waitcnt lgkmcnt(0)
	v_add_f32_e32 v3, v3, v185
	ds_read_b32 v170, v115 offset:20480
	ds_read_b32 v171, v116 offset:20480
	ds_read_b32 v172, v117 offset:20480
	ds_read_b32 v173, v118 offset:20480
	ds_read_b32 v174, v119 offset:20480
	ds_read_b32 v175, v120 offset:20480
	ds_read_b32 v176, v121 offset:20480
	ds_read_b32 v177, v122 offset:20480
	ds_read_b32 v178, v123 offset:20480
	ds_read_b32 v179, v124 offset:20480
	ds_read_b32 v180, v125 offset:20480
	ds_read_b32 v181, v126 offset:20480
	ds_read_b32 v182, v127 offset:20480
	ds_read_b32 v183, v128 offset:20480
	ds_read_b32 v184, v129 offset:20480
	s_waitcnt lgkmcnt(14)
	v_add_f32_e32 v3, v3, v170
	s_waitcnt lgkmcnt(13)
	v_add_f32_e32 v3, v3, v171
	s_waitcnt lgkmcnt(12)
	v_add_f32_e32 v3, v3, v172
	s_waitcnt lgkmcnt(11)
	v_add_f32_e32 v3, v3, v173
	s_waitcnt lgkmcnt(10)
	v_add_f32_e32 v3, v3, v174
	s_waitcnt lgkmcnt(9)
	v_add_f32_e32 v3, v3, v175
	s_waitcnt lgkmcnt(8)
	v_add_f32_e32 v3, v3, v176
	s_waitcnt lgkmcnt(7)
	v_add_f32_e32 v3, v3, v177
	s_waitcnt lgkmcnt(6)
	v_add_f32_e32 v3, v3, v178
	s_waitcnt lgkmcnt(5)
	v_add_f32_e32 v3, v3, v179
	s_waitcnt lgkmcnt(4)
	v_add_f32_e32 v3, v3, v180
	s_waitcnt lgkmcnt(3)
	v_add_f32_e32 v3, v3, v181
	s_waitcnt lgkmcnt(2)
	v_add_f32_e32 v3, v3, v182
	s_waitcnt lgkmcnt(1)
	v_add_f32_e32 v3, v3, v183
	s_waitcnt lgkmcnt(0)
	v_add_f32_e32 v6, v3, v184
	v_mad_u64_u32 v[4:5], s[36:37], v22, 5, v[34:35]
	v_mad_u64_u32 v[2:3], s[36:37], v4, s3, v[2:3]
	v_ashrrev_i32_e32 v3, 31, v2
	v_lshl_add_u64 v[2:3], v[2:3], 2, s[96:97]
	global_store_dword v[2:3], v6, off
	s_branch .LBB0_8

.LBB0_461:
	s_or_b64 exec, exec, s[4:5]
	v_and_b32_e32 v184, 7, v2
	s_and_saveexec_b64 s[6:7], s[0:1]
	s_cbranch_execz .LBB0_464
	v_mul_u32_u24_e32 v2, 0x1d1, v184
	v_readlane_b32 s8, v245, 0
	v_add_lshl_u32 v2, v130, v2, 2
	v_mov_b32_e32 v3, v133
	v_readlane_b32 s9, v245, 1
	v_mov_b32_e32 v4, v175
	v_mov_b32_e32 v5, v174
	v_lshl_add_u64 v[2:3], s[8:9], 0, v[2:3]
	s_mov_b64 s[8:9], 0
	v_readlane_b32 s10, v245, 2
	v_readlane_b32 s11, v245, 3
	v_readlane_b32 s12, v245, 4
	v_readlane_b32 s13, v245, 5
	v_readlane_b32 s14, v245, 6
	v_readlane_b32 s15, v245, 7
	v_readlane_b32 s16, v245, 8
	v_readlane_b32 s17, v245, 9
	v_readlane_b32 s18, v245, 10
	v_readlane_b32 s19, v245, 11
	v_readlane_b32 s20, v245, 12
	v_readlane_b32 s21, v245, 13
	v_readlane_b32 s22, v245, 14
	v_readlane_b32 s23, v245, 15
	global_load_dword v7, v[2:3], off
	s_movk_i32 s3, 0xd1
	v_cmp_gt_u32_e64 s[4:5], s3, v130
	s_and_saveexec_b64 s[8:9], s[4:5]
	global_load_dword v4, v[2:3], off offset:1024
	s_mov_b64 exec, s[8:9]
	s_waitcnt vmcnt(0)
	v_mul_f32_e32 v7, 0x3fb8aa3b, v7
	ds_write_b32 v5, v7
	s_and_saveexec_b64 s[8:9], s[4:5]
	v_mul_f32_e32 v4, 0x3fb8aa3b, v4
	ds_write_b32 v5, v4 offset:1024
	s_mov_b64 exec, s[8:9]
.LBB0_464:
	s_or_b64 exec, exec, s[6:7]
	v_ashrrev_i32_e32 v147, 31, v146
	v_lshlrev_b64 v[150:151], 10, v[146:147]
	v_lshl_add_u64 v[2:3], s[24:25], 0, v[150:151]
	v_lshlrev_b32_e32 v4, 7, v184
	v_mov_b32_e32 v5, v133
	v_lshl_add_u64 v[2:3], v[2:3], 0, v[4:5]
	v_lshl_add_u64 v[2:3], v[2:3], 0, v[134:135]
	global_load_dwordx4 v[98:101], v[2:3], off
	global_load_dwordx4 v[102:105], v[2:3], off offset:32
	global_load_dwordx4 v[106:109], v[2:3], off offset:64
	global_load_dwordx4 v[110:113], v[2:3], off offset:96
	s_and_saveexec_b64 s[4:5], vcc
	s_xor_b64 s[4:5], exec, s[4:5]
	v_ashrrev_i32_e32 v4, 6, v148
	v_ashrrev_i32_e32 v149, 31, v148
	v_ashrrev_i32_e32 v5, 31, v4
	v_mad_u64_u32 v[2:3], s[6:7], v184, s26, v[148:149]
	v_mad_u64_u32 v[4:5], s[6:7], v184, s33, v[4:5]
	v_lshlrev_b64 v[2:3], 7, v[2:3]
	v_lshlrev_b64 v[4:5], 13, v[4:5]
	v_lshl_add_u64 v[2:3], s[88:89], 0, v[2:3]
	v_lshl_add_u64 v[4:5], s[90:91], 0, v[4:5]
	s_or_saveexec_b64 s[4:5], s[4:5]
	v_lshl_or_b32 v34, v6, 3, v184
	v_ashrrev_i32_e32 v35, 31, v34
	s_xor_b64 exec, exec, s[4:5]
	v_lshlrev_b64 v[4:5], 16, v[34:35]
	v_lshl_add_u64 v[2:3], s[80:81], 0, v[4:5]
	v_lshl_add_u64 v[4:5], s[92:93], 0, v[4:5]
	s_or_b64 exec, exec, s[4:5]
	v_lshl_add_u64 v[6:7], v[2:3], 0, v[132:133]
	v_lshl_add_u64 v[2:3], v[2:3], 0, v[142:143]
	v_lshl_add_u64 v[6:7], v[6:7], 0, v[138:139]
	v_lshl_add_u64 v[2:3], v[2:3], 0, v[138:139]
	global_load_dwordx4 v[6:9], v[6:7], off
	s_nop 0
	global_load_dwordx4 v[10:13], v[2:3], off
	v_lshl_add_u64 v[2:3], v[4:5], 0, v[132:133]
	v_lshl_add_u64 v[4:5], v[4:5], 0, v[142:143]
	v_lshl_add_u64 v[2:3], v[2:3], 0, v[138:139]
	v_lshl_add_u64 v[14:15], v[4:5], 0, v[138:139]
	global_load_dwordx4 v[2:5], v[2:3], off
	s_nop 0
	global_load_dwordx4 v[14:17], v[14:15], off
	s_and_saveexec_b64 s[4:5], vcc
	s_xor_b64 s[4:5], exec, s[4:5]
	s_cbranch_execz .LBB0_470
	v_add_u32_e32 v60, 64, v148
	v_ashrrev_i32_e32 v61, 31, v60
	v_mad_u64_u32 v[62:63], s[6:7], v184, s26, v[60:61]
	v_ashrrev_i32_e32 v60, 6, v60
	v_ashrrev_i32_e32 v61, 31, v60
	v_mad_u64_u32 v[60:61], s[6:7], v184, s33, v[60:61]
	v_lshlrev_b64 v[62:63], 7, v[62:63]
	v_lshlrev_b64 v[60:61], 13, v[60:61]
	v_lshl_add_u64 v[36:37], s[88:89], 0, v[62:63]
	v_lshl_add_u64 v[38:39], s[90:91], 0, v[60:61]
.LBB0_470:
	s_andn2_saveexec_b64 s[4:5], s[4:5]
	v_lshlrev_b64 v[60:61], 16, v[34:35]
	v_lshl_add_u64 v[62:63], s[80:81], 0, v[60:61]
	s_mov_b64 s[6:7], 0x2000
	v_lshl_add_u64 v[60:61], s[92:93], 0, v[60:61]
	v_lshl_add_u64 v[36:37], v[62:63], 0, s[6:7]
	v_lshl_add_u64 v[38:39], v[60:61], 0, s[6:7]
	s_or_b64 exec, exec, s[4:5]
	v_lshl_add_u64 v[60:61], v[38:39], 0, v[142:143]
	v_lshl_add_u64 v[60:61], v[60:61], 0, v[138:139]
	v_lshl_add_u64 v[62:63], v[38:39], 0, v[132:133]
	v_lshl_add_u64 v[62:63], v[62:63], 0, v[138:139]
	global_load_dwordx4 v[114:117], v[60:61], off
	global_load_dwordx4 v[118:121], v[62:63], off
	v_lshl_add_u64 v[60:61], v[36:37], 0, v[142:143]
	v_lshl_add_u64 v[60:61], v[60:61], 0, v[138:139]
	v_lshl_add_u64 v[62:63], v[36:37], 0, v[132:133]
	v_lshl_add_u64 v[62:63], v[62:63], 0, v[138:139]
	global_load_dwordx4 v[122:125], v[60:61], off
	global_load_dwordx4 v[126:129], v[62:63], off
	s_waitcnt vmcnt(7)
	ds_write_b128 v176, v[6:9]
	s_waitcnt vmcnt(6)
	ds_write_b128 v177, v[10:13]
	s_waitcnt vmcnt(5)
	ds_write2_b64 v179, v[2:3], v[4:5] offset0:128 offset1:130
	s_waitcnt vmcnt(4)
	ds_write2_b64 v180, v[14:15], v[16:17] offset0:128 offset1:130
	v_mov_b32_e32 v16, v133
	v_mov_b32_e32 v17, v133
	v_mov_b32_e32 v2, v133
	v_mov_b32_e32 v3, v133
	v_mov_b32_e32 v4, v133
	v_mov_b32_e32 v5, v133
	v_mov_b32_e32 v6, v133
	v_mov_b32_e32 v7, v133
	v_mov_b32_e32 v8, v133
	v_mov_b32_e32 v9, v133
	v_mov_b32_e32 v10, v133
	v_mov_b32_e32 v11, v133
	v_mov_b32_e32 v12, v133
	v_mov_b32_e32 v13, v133
	v_mov_b32_e32 v14, v133
	v_mov_b32_e32 v15, v133
	v_mov_b64_e32 v[32:33], v[16:17]
	v_cmp_lt_i32_e32 vcc, 0, v183
	v_mov_b32_e32 v149, 0
	v_mov_b64_e32 v[30:31], v[14:15]
	v_mov_b64_e32 v[28:29], v[12:13]
	v_mov_b64_e32 v[26:27], v[10:11]
	v_mov_b64_e32 v[24:25], v[8:9]
	v_mov_b64_e32 v[22:23], v[6:7]
	v_mov_b64_e32 v[20:21], v[4:5]
	v_mov_b64_e32 v[18:19], v[2:3]
	s_and_saveexec_b64 s[82:83], vcc
	s_cbranch_execz .LBB0_456
	v_lshlrev_b64 v[2:3], 16, v[34:35]
	v_lshl_add_u64 v[156:157], s[80:81], 0, v[2:3]
	v_lshl_add_u64 v[158:159], s[92:93], 0, v[2:3]
	v_sub_u32_e32 v2, v171, v42
	v_lshl_add_u32 v187, v2, 2, v160
	v_sub_u32_e32 v2, v171, v41
	v_and_b32_e32 v3, -16, v2
	s_movk_i32 s3, 0xffe0
	v_cmp_eq_u32_e64 s[6:7], s3, v3
	s_movk_i32 s3, 0xffef
	v_add_u32_e32 v4, 1, v2
	v_cmp_lt_u32_e64 s[38:39], s3, v2
	s_movk_i32 s3, 0xffd0
	v_cmp_gt_u32_e64 s[8:9], 16, v4
	v_add_u32_e32 v4, 33, v2
	v_cmp_eq_u32_e64 s[40:41], s3, v3
	v_add_u32_e32 v3, 17, v2
	v_cmp_gt_u32_e64 s[10:11], 16, v4
	v_add_u32_e32 v4, 2, v2
	v_cmp_gt_u32_e64 s[42:43], 16, v3
	v_add_u32_e32 v3, 49, v2
	v_cmp_gt_u32_e64 s[12:13], 16, v4
	v_add_u32_e32 v4, 34, v2
	v_cmp_gt_u32_e64 s[44:45], 16, v3
	v_add_u32_e32 v3, 18, v2
	v_cmp_gt_u32_e64 s[14:15], 16, v4
	v_add_u32_e32 v4, 3, v2
	v_cmp_gt_u32_e64 s[46:47], 16, v3
	v_add_u32_e32 v3, 50, v2
	v_cmp_gt_u32_e64 s[16:17], 16, v4
	v_add_u32_e32 v4, 35, v2
	v_cmp_gt_u32_e64 s[48:49], 16, v3
	v_add_u32_e32 v3, 19, v2
	v_cmp_gt_u32_e64 s[18:19], 16, v4
	v_add_u32_e32 v4, 8, v2
	v_cmp_gt_u32_e64 s[50:51], 16, v3
	v_add_u32_e32 v3, 51, v2
	v_cmp_gt_u32_e64 s[20:21], 16, v4
	v_add_u32_e32 v4, 40, v2
	v_cmp_gt_u32_e64 s[52:53], 16, v3
	v_add_u32_e32 v3, 24, v2
	v_cmp_gt_u32_e64 s[22:23], 16, v4
	v_add_u32_e32 v4, 9, v2
	v_cmp_gt_u32_e64 s[54:55], 16, v3
	v_add_u32_e32 v3, 56, v2
	v_cmp_gt_u32_e64 s[24:25], 16, v4
	v_add_u32_e32 v4, 41, v2
	v_cmp_gt_u32_e64 s[56:57], 16, v3
	v_add_u32_e32 v3, 25, v2
	v_cmp_gt_u32_e64 s[26:27], 16, v4
	v_add_u32_e32 v4, 10, v2
	v_cmp_gt_u32_e64 s[58:59], 16, v3
	v_add_u32_e32 v3, 57, v2
	v_cmp_gt_u32_e64 s[28:29], 16, v4
	v_add_u32_e32 v4, 42, v2
	v_cmp_gt_u32_e64 s[60:61], 16, v3
	v_add_u32_e32 v3, 26, v2
	v_cmp_gt_u32_e64 s[30:31], 16, v4
	v_add_u32_e32 v4, 11, v2
	v_cmp_gt_u32_e64 s[62:63], 16, v3
	v_add_u32_e32 v3, 58, v2
	v_cmp_gt_u32_e64 s[4:5], 16, v2
	v_cmp_gt_u32_e64 s[34:35], 16, v4
	v_add_u32_e32 v4, 43, v2
	v_cmp_gt_u32_e64 s[64:65], 16, v3
	v_add_u32_e32 v3, 27, v2
	v_add_u32_e32 v2, 59, v2
	v_cmp_gt_u32_e64 s[66:67], 16, v3
	v_cmp_gt_u32_e64 s[68:69], 16, v2
	v_mul_u32_u24_e32 v2, 31, v145
	v_mul_u32_u24_e32 v3, 31, v40
	v_sub_u32_e32 v2, v2, v3
	v_mov_b32_e32 v16, v133
	v_mov_b32_e32 v17, v133
	v_cmp_gt_u32_e64 s[36:37], 16, v4
	v_subrev_u32_e32 v188, 31, v2
	v_mov_b32_e32 v2, v133
	v_mov_b32_e32 v3, v133
	v_mov_b32_e32 v4, v133
	v_mov_b32_e32 v5, v133
	v_mov_b32_e32 v6, v133
	v_mov_b32_e32 v7, v133
	v_mov_b32_e32 v8, v133
	v_mov_b32_e32 v9, v133
	v_mov_b32_e32 v10, v133
	v_mov_b32_e32 v11, v133
	v_mov_b32_e32 v12, v133
	v_mov_b32_e32 v13, v133
	v_mov_b32_e32 v14, v133
	v_mov_b32_e32 v15, v133
	v_mov_b64_e32 v[32:33], v[16:17]
	v_add_u32_e32 v185, -1, v183
	v_mul_hi_u32_u24_e32 v153, 0x6000, v184
	v_mul_u32_u24_e32 v152, 0x6000, v184
	v_mul_hi_u32_u24_e32 v155, 0x180, v184
	v_mul_u32_u24_e32 v154, 0x180, v184
	v_add_u32_e32 v186, 8, v182
	v_add_u32_e32 v189, -8, v145
	s_mov_b32 s3, 0
	v_mov_b32_e32 v190, 0xff800000
	v_mov_b32_e32 v149, 0
	s_mov_b64 s[70:71], 0
	s_xor_b64 s[86:87], s[0:1], -1
	v_mov_b64_e32 v[30:31], v[14:15]
	v_mov_b64_e32 v[28:29], v[12:13]
	v_mov_b64_e32 v[26:27], v[10:11]
	v_mov_b64_e32 v[24:25], v[8:9]
	v_mov_b64_e32 v[22:23], v[6:7]
	v_mov_b64_e32 v[20:21], v[4:5]
	v_mov_b64_e32 v[18:19], v[2:3]
	v_mov_b32_e32 v36, 0
	v_mov_b32_e32 v38, 0
	s_mov_b64 s[72:73], s[86:87]
	s_and_saveexec_b64 s[76:77], s[72:73]
	s_xor_b64 s[72:73], exec, s[76:77]
	s_cbranch_execz .Laddr478_a
	v_add_u32_e32 v34, v36, v145
	v_lshl_add_u32 v34, v34, 6, v181
	v_cndmask_b32_e64 v34, v38, v34, s[0:1]
	v_add_u32_e32 v36, v34, v148
	v_ashrrev_i32_e32 v37, 31, v36
	v_lshl_add_u64 v[34:35], v[152:153], 0, v[36:37]
	v_ashrrev_i32_e32 v36, 6, v36
	v_lshlrev_b64 v[34:35], 7, v[34:35]
	v_ashrrev_i32_e32 v37, 31, v36
	v_lshl_add_u64 v[34:35], s[88:89], 0, v[34:35]
	v_lshl_add_u64 v[36:37], v[154:155], 0, v[36:37]
